# v21 + L8 (FFN-down) EpiNorm residual step with row loads batched 8-deep like L4 (same arithmetic); v21 = v15 + MLA loop instruction trims
# speedup vs baseline: 1.0107x; 1.0011x over previous
; #define LAS __attribute__((address_space(3)))
; __global__ void __launch_bounds__(NTHR, 2) fwd_megakernel(Params P) {
;     ...
;             for (int unit = bid; unit < 1024; unit += G) {
;                 const int b = unit >> 6, h = (unit >> 4) & 3, qb = unit & 15;
;                 const size_t tb = (size_t)b * SEQ;
;                 bf16x8 qf[2][3];
; #pragma unroll
;                 for (int t = 0; t < 2; ++t) { const size_t row = tb + qb * 256 + 32 * wave + 16 * t + i; const float sc = rq[row] * qscale;
;                     const bf16_t* qp = QB + row * 384 + 96 * h + 8 * g4;
; #pragma unroll
;                     for (int ks = 0; ks < 3; ++ks) qf[t][ks] = load_q(qp + 32 * ks, sc); }
;                 f32x4 o[2][4];
; #pragma unroll
;                 for (int t = 0; t < 2; ++t)
; #pragma unroll
;                     for (int db = 0; db < 4; ++db) o[t][db] = (f32x4){0.f, 0.f, 0.f, 0.f};
;                 unsigned doff[6]; unsigned dz = 0u;
; #pragma unroll
;                 for (int j = 0; j < 6; ++j) {
;                     const int pc = wave + 8 * j;
;                     if (pc < 28) { const int off = pc * 1024 + lane * 16, row = off / S96, col = off - row * S96;
;                         if (col >= 128 && col < 192) { doff[j] = (unsigned)(row * (ZLD * 2) + (col - 128)); dz |= 1u << j; }
;                         else doff[j] = (unsigned)(row * 1024 + (col < 128 ? col : 0)); }
;                     else { const int off = (pc - 28) * 1024 + lane * 16, row = off / S64, col = off - row * S64;
;                         doff[j] = (unsigned)(row * 1024 + 128 + (col < 128 ? col : 0)); }
;                 }
;                 auto dma = [&](int c, int buf) {
;                     const size_t key0 = tb + (size_t)c * 128;
;                     const char* kvb = (const char*)(KVB + key0 * 512 + 128 * h);
;                     const char* zkr = (const char*)(Z + key0 * ZLD + ZC_KR);
; #pragma unroll
;                     for (int j = 0; j < 6; ++j) {
;                         const int pc = wave + 8 * j;
;                         const char* src = (((dz >> j) & 1u) ? zkr : kvb) + doff[j];
;                         __builtin_amdgcn_global_load_lds((const unsigned*)src, (LAS unsigned*)(lds + buf * BUF_BYTES + pc * 1024), 16, 0, 0);
;                     }
;                 };
.LBB0_648:
	s_ashr_i32 s16, s25, 6
	s_ashr_i32 s17, s16, 31
	s_lshl_b32 s20, s25, 8
	s_bfe_u32 s35, s25, 0x20004
	s_lshl_b64 s[0:1], s[16:17], 12
	s_and_b32 s20, s20, 0xf00
	s_or_b32 s22, s0, s20
	s_mov_b32 s23, s1
	s_mul_i32 s20, s35, 0xc0
	v_lshl_add_u64 v[140:141], s[22:23], 0, v[122:123]
	v_lshl_add_u64 v[0:1], v[126:127], 0, s[20:21]
	v_mad_u64_u32 v[18:19], s[22:23], v140, s65, v[0:1]
	v_mov_b32_e32 v0, v19
	v_or_b32_e32 v142, 16, v140
	v_mov_b32_e32 v143, v141
	s_movk_i32 s20, 0x3000
	v_lshl_add_u64 v[2:3], v[140:141], 2, s[88:89]
	v_mad_u64_u32 v[14:15], s[22:23], v141, s65, v[0:1]
	v_lshl_add_u64 v[0:1], v[142:143], 2, s[88:89]
	v_add_co_u32_e32 v16, vcc, s20, v18
	v_mov_b32_e32 v19, v14
	global_load_dword v26, v[2:3], off
	global_load_dword v27, v[0:1], off
	s_nop 0
	global_load_dwordx4 v[0:3], v[18:19], off
	global_load_dwordx4 v[4:7], v[18:19], off offset:64
	global_load_dwordx4 v[8:11], v[18:19], off offset:128
	v_addc_co_u32_e32 v17, vcc, 0, v14, vcc
	global_load_dwordx4 v[14:17], v[16:17], off
	s_lshl_b32 s29, s35, 8
	s_lshl_b64 s[26:27], s[16:17], 22
	s_add_u32 s17, s76, s26
	s_mov_b64 s[22:23], 0x3000
	s_addc_u32 s20, s77, s27
	v_lshl_add_u64 v[22:23], v[18:19], 0, s[22:23]
	s_add_u32 s22, s17, s29
	s_addc_u32 s20, s20, 0
	s_mul_hi_i32 s17, s16, 0x1800000
	s_mul_i32 s16, s16, 0x1800000
	s_add_u32 s23, s72, s16
	s_addc_u32 s30, s73, s17
	s_add_u32 s23, s23, 0x1700
	s_addc_u32 s30, s30, 0
	s_mov_b32 m0, s18
	global_load_dwordx4 v[18:21], v[22:23], off offset:64
	s_nop 0
	global_load_dwordx4 v[22:25], v[22:23], off offset:128
	s_bitset1_b32 s0, 7
	v_readlane_b32 s15, v254, 56
	s_mov_b32 s36, 0
	s_waitcnt vmcnt(7)
	v_mul_f32_e32 v28, 0x3e16c740, v26
	s_waitcnt vmcnt(6)
	v_mul_f32_e32 v26, 0x3e16c740, v27
	s_waitcnt vmcnt(5)
	v_lshlrev_b32_e32 v30, 16, v0
	v_and_b32_e32 v31, 0xffff0000, v0
	v_lshlrev_b32_e32 v0, 16, v1
	v_and_b32_e32 v1, 0xffff0000, v1
	v_lshlrev_b32_e32 v32, 16, v2
	v_and_b32_e32 v33, 0xffff0000, v2
	v_lshlrev_b32_e32 v2, 16, v3
	v_and_b32_e32 v3, 0xffff0000, v3
	s_waitcnt vmcnt(4)
	v_lshlrev_b32_e32 v34, 16, v4
	v_and_b32_e32 v35, 0xffff0000, v4
	v_lshlrev_b32_e32 v4, 16, v5
	v_and_b32_e32 v5, 0xffff0000, v5
	v_lshlrev_b32_e32 v36, 16, v6
	v_and_b32_e32 v37, 0xffff0000, v6
	v_lshlrev_b32_e32 v6, 16, v7
	v_and_b32_e32 v7, 0xffff0000, v7
	s_waitcnt vmcnt(3)
	v_lshlrev_b32_e32 v38, 16, v8
	v_and_b32_e32 v39, 0xffff0000, v8
	v_lshlrev_b32_e32 v8, 16, v9
	v_and_b32_e32 v9, 0xffff0000, v9
	v_lshlrev_b32_e32 v40, 16, v10
	v_and_b32_e32 v41, 0xffff0000, v10
	v_lshlrev_b32_e32 v10, 16, v11
	v_and_b32_e32 v11, 0xffff0000, v11
	s_waitcnt vmcnt(2)
	v_lshlrev_b32_e32 v44, 16, v15
	v_pk_mul_f32 v[30:31], v[28:29], v[30:31] op_sel_hi:[0,1]
	v_pk_mul_f32 v[0:1], v[28:29], v[0:1] op_sel_hi:[0,1]
	v_pk_mul_f32 v[32:33], v[28:29], v[32:33] op_sel_hi:[0,1]
	v_pk_mul_f32 v[2:3], v[28:29], v[2:3] op_sel_hi:[0,1]
	v_pk_mul_f32 v[34:35], v[28:29], v[34:35] op_sel_hi:[0,1]
	v_pk_mul_f32 v[46:47], v[28:29], v[4:5] op_sel_hi:[0,1]
	v_pk_mul_f32 v[36:37], v[28:29], v[36:37] op_sel_hi:[0,1]
	v_pk_mul_f32 v[48:49], v[28:29], v[6:7] op_sel_hi:[0,1]
	v_pk_mul_f32 v[38:39], v[28:29], v[38:39] op_sel_hi:[0,1]
	v_pk_mul_f32 v[50:51], v[28:29], v[8:9] op_sel_hi:[0,1]
	v_pk_mul_f32 v[40:41], v[28:29], v[40:41] op_sel_hi:[0,1]
	v_pk_mul_f32 v[28:29], v[28:29], v[10:11] op_sel_hi:[0,1]
	v_and_b32_e32 v45, 0xffff0000, v15
	v_cvt_pk_bf16_f32 v11, v2, v3
	v_cvt_pk_bf16_f32 v3, v28, v29
	v_pk_mul_f32 v[28:29], v[26:27], v[44:45] op_sel_hi:[0,1]
	v_lshlrev_b32_e32 v42, 16, v14
	v_and_b32_e32 v43, 0xffff0000, v14
	v_cvt_pk_bf16_f32 v15, v28, v29
	v_lshlrev_b32_e32 v28, 16, v16
	v_and_b32_e32 v29, 0xffff0000, v16
	v_pk_mul_f32 v[42:43], v[26:27], v[42:43] op_sel_hi:[0,1]
	v_cvt_pk_bf16_f32 v8, v30, v31
	v_cvt_pk_bf16_f32 v10, v32, v33
	v_pk_mul_f32 v[28:29], v[26:27], v[28:29] op_sel_hi:[0,1]
	v_mov_b32_e32 v27, s30
	v_mov_b32_e32 v30, s20
	v_mov_b32_e32 v31, s23
	v_mov_b32_e32 v32, s22
	v_cvt_pk_bf16_f32 v16, v28, v29
	v_cndmask_b32_e64 v29, v27, v30, s[2:3]
	v_cndmask_b32_e64 v28, v31, v32, s[2:3]
	v_lshl_add_u64 v[28:29], v[28:29], 0, v[128:129]
	global_load_lds_dwordx4 v[28:29], off
	v_cndmask_b32_e64 v29, v27, v30, s[4:5]
	v_cndmask_b32_e64 v28, v31, v32, s[4:5]
	v_lshl_add_u64 v[28:29], v[28:29], 0, v[130:131]
	s_add_i32 m0, s18, 0x2000
	s_lshl_b64 s[22:23], s[0:1], 10
	global_load_lds_dwordx4 v[28:29], off
	v_cndmask_b32_e64 v29, v27, v30, s[6:7]
	v_cndmask_b32_e64 v28, v31, v32, s[6:7]
	v_lshl_add_u64 v[28:29], v[28:29], 0, v[132:133]
	s_add_i32 m0, s18, 0x4000
	s_mulk_i32 s1, 0x1800
	global_load_lds_dwordx4 v[28:29], off
	v_cndmask_b32_e64 v29, v27, v30, s[8:9]
	v_cndmask_b32_e64 v28, v31, v32, s[8:9]
	v_lshl_add_u64 v[28:29], v[28:29], 0, v[134:135]
	s_add_i32 m0, s18, 0x6000
	s_waitcnt vmcnt(0)
; #define LAS __attribute__((address_space(3)))
; __global__ void __launch_bounds__(NTHR, 2) fwd_megakernel(Params P) {
;     ...
;                 constexpr float THR = 8.0f;
;                 bf16x8 kf[6]; f32x4 s0[2], s1[2], negm[2], lacc[2];
;                 const bf16x8 ones = {0x3f80, 0x3f80, 0x3f80, 0x3f80, 0x3f80, 0x3f80, 0x3f80, 0x3f80};
; #pragma unroll
;                 for (int t = 0; t < 2; ++t) { negm[t] = (f32x4){0.f, 0.f, 0.f, 0.f}; lacc[t] = (f32x4){0.f, 0.f, 0.f, 0.f}; }
;                 auto kload = [&](LAS const unsigned char* Kl, int kb) {
;                     LAS const unsigned char* kp = Kl + (kb + i) * S96 + g4 * 16;
; #pragma unroll
;                     for (int ks = 0; ks < 3; ++ks) { kf[2 * ks] = *(LAS const bf16x8*)(kp + ks * 64); kf[2 * ks + 1] = *(LAS const bf16x8*)(kp + 16 * S96 + ks * 64); }
;                 };
;                 auto qkm = [&]() {
; #pragma unroll
;                     for (int t = 0; t < 2; ++t) {
;                         s0[t] = __builtin_amdgcn_mfma_f32_16x16x32_bf16(kf[0], qf[t][0], negm[t], 0, 0, 0);
;                         s1[t] = __builtin_amdgcn_mfma_f32_16x16x32_bf16(kf[1], qf[t][0], negm[t], 0, 0, 0);
;                     }
; #pragma unroll
;                     for (int ks = 1; ks < 3; ++ks)
; #pragma unroll
;                         for (int t = 0; t < 2; ++t) {
;                             s0[t] = __builtin_amdgcn_mfma_f32_16x16x32_bf16(kf[2 * ks], qf[t][ks], s0[t], 0, 0, 0);
;                             s1[t] = __builtin_amdgcn_mfma_f32_16x16x32_bf16(kf[2 * ks + 1], qf[t][ks], s1[t], 0, 0, 0);
;                         }
;                 };
;     ...
;                 dma(0, 0); dma(1, 1);
;                 asm volatile("s_waitcnt vmcnt(0)" ::: "memory"); __syncthreads();
;                 kload(lds, 0); qkm();
	v_and_b32_e32 v33, 0xffff0000, v18
	global_load_lds_dwordx4 v[28:29], off
	v_cndmask_b32_e64 v29, v27, v30, s[10:11]
	v_cndmask_b32_e64 v28, v31, v32, s[10:11]
	v_lshl_add_u64 v[28:29], v[28:29], 0, v[136:137]
	s_add_i32 m0, s18, 0x8000
	v_cvt_pk_bf16_f32 v4, v34, v35
	global_load_lds_dwordx4 v[28:29], off
	s_add_i32 m0, s18, 0xa000
	s_add_u32 s20, s76, s22
	s_addc_u32 s22, s77, s23
	s_add_u32 s20, s20, s29
	s_mul_hi_u32 s23, s0, 0x1800
	s_addc_u32 s22, s22, 0
	s_add_i32 s23, s23, s1
	s_mulk_i32 s0, 0x1800
	s_add_u32 s0, s72, s0
	s_addc_u32 s1, s73, s23
	s_add_u32 s0, s0, 0x1700
	v_cndmask_b32_e64 v29, v27, v30, s[12:13]
	v_cndmask_b32_e64 v28, v31, v32, s[12:13]
	s_addc_u32 s1, s1, 0
	v_lshl_add_u64 v[28:29], v[28:29], 0, v[138:139]
	v_mov_b32_e32 v27, s1
	v_mov_b32_e32 v30, s22
	v_mov_b32_e32 v31, s0
	v_mov_b32_e32 v32, s20
	global_load_lds_dwordx4 v[28:29], off
	v_cndmask_b32_e64 v29, v27, v30, s[2:3]
	v_cndmask_b32_e64 v28, v31, v32, s[2:3]
	v_lshl_add_u64 v[28:29], v[28:29], 0, v[128:129]
	s_add_i32 m0, s18, 0xc000
	v_cvt_pk_bf16_f32 v6, v36, v37
	global_load_lds_dwordx4 v[28:29], off
	v_cndmask_b32_e64 v29, v27, v30, s[4:5]
	v_cndmask_b32_e64 v28, v31, v32, s[4:5]
	v_lshl_add_u64 v[28:29], v[28:29], 0, v[130:131]
	s_add_i32 m0, s18, 0xe000
	v_lshlrev_b32_e32 v52, 16, v20
	global_load_lds_dwordx4 v[28:29], off
	v_cndmask_b32_e64 v29, v27, v30, s[6:7]
	v_cndmask_b32_e64 v28, v31, v32, s[6:7]
	v_lshl_add_u64 v[28:29], v[28:29], 0, v[132:133]
	s_add_i32 m0, s18, 0x10000
	v_and_b32_e32 v53, 0xffff0000, v20
	global_load_lds_dwordx4 v[28:29], off
	v_cndmask_b32_e64 v29, v27, v30, s[8:9]
	v_cndmask_b32_e64 v28, v31, v32, s[8:9]
	v_lshl_add_u64 v[28:29], v[28:29], 0, v[134:135]
	s_add_i32 m0, s18, 0x12000
	v_pk_mul_f32 v[52:53], v[26:27], v[52:53] op_sel_hi:[0,1]
	global_load_lds_dwordx4 v[28:29], off
	v_cndmask_b32_e64 v29, v27, v30, s[10:11]
	v_cndmask_b32_e64 v28, v31, v32, s[10:11]
	v_lshl_add_u64 v[28:29], v[28:29], 0, v[136:137]
	s_add_i32 m0, s18, 0x14000
	v_cvt_pk_bf16_f32 v20, v52, v53
	global_load_lds_dwordx4 v[28:29], off
	v_cndmask_b32_e64 v29, v27, v30, s[12:13]
	v_cndmask_b32_e64 v28, v31, v32, s[12:13]
	v_lshl_add_u64 v[28:29], v[28:29], 0, v[138:139]
	s_add_i32 m0, s18, 0x16000
	v_lshlrev_b32_e32 v32, 16, v18
	global_load_lds_dwordx4 v[28:29], off
	v_lshlrev_b32_e32 v28, 16, v17
	v_and_b32_e32 v29, 0xffff0000, v17
	v_pk_mul_f32 v[28:29], v[26:27], v[28:29] op_sel_hi:[0,1]
	s_waitcnt vmcnt(0)
	s_waitcnt vmcnt(0) lgkmcnt(0)
	s_barrier
	v_pk_mul_f32 v[36:37], v[26:27], v[32:33] op_sel_hi:[0,1]
	ds_read_b128 v[32:35], v144 offset:3584
	v_cvt_pk_bf16_f32 v17, v28, v29
	ds_read_b128 v[28:31], v144
	ds_read_b128 v[52:55], v144 offset:3648
	v_cvt_pk_bf16_f32 v9, v0, v1
	v_cvt_pk_bf16_f32 v0, v38, v39
	v_cvt_pk_bf16_f32 v18, v36, v37
	ds_read_b128 v[36:39], v144 offset:64
	v_lshlrev_b32_e32 v44, 16, v19
	v_and_b32_e32 v45, 0xffff0000, v19
	v_lshlrev_b32_e32 v56, 16, v21
	v_and_b32_e32 v57, 0xffff0000, v21
	v_cvt_pk_bf16_f32 v14, v42, v43
	v_pk_mul_f32 v[44:45], v[26:27], v[44:45] op_sel_hi:[0,1]
	v_pk_mul_f32 v[56:57], v[26:27], v[56:57] op_sel_hi:[0,1]
	v_cvt_pk_bf16_f32 v5, v46, v47
	v_cvt_pk_bf16_f32 v7, v48, v49
	v_cvt_pk_bf16_f32 v1, v50, v51
	v_cvt_pk_bf16_f32 v19, v44, v45
	ds_read_b128 v[44:47], v144 offset:128
	s_waitcnt lgkmcnt(4)
	v_mfma_f32_16x16x32_bf16 v[48:51], v[32:35], v[8:11], 0
	v_cvt_pk_bf16_f32 v21, v56, v57
	ds_read_b128 v[56:59], v144 offset:3712
	v_cvt_pk_bf16_f32 v2, v40, v41
	v_mfma_f32_16x16x32_bf16 v[32:35], v[32:35], v[14:17], 0
	v_lshlrev_b32_e32 v60, 16, v22
	v_and_b32_e32 v61, 0xffff0000, v22
	v_pk_mul_f32 v[60:61], v[26:27], v[60:61] op_sel_hi:[0,1]
	s_waitcnt lgkmcnt(4)
	v_mfma_f32_16x16x32_bf16 v[40:43], v[28:31], v[8:11], 0
	v_cvt_pk_bf16_f32 v22, v60, v61
	v_lshlrev_b32_e32 v60, 16, v23
	v_and_b32_e32 v61, 0xffff0000, v23
	v_mfma_f32_16x16x32_bf16 v[28:31], v[28:31], v[14:17], 0
	v_readlane_b32 s0, v254, 54
	s_add_u32 s0, s0, s16
	v_readlane_b32 s1, v254, 55
	s_waitcnt lgkmcnt(3)
	v_mfma_f32_16x16x32_bf16 v[48:51], v[52:55], v[4:7], v[48:51]
	s_mov_b32 s22, s21
	s_mov_b32 s23, s21
	s_addc_u32 s1, s1, s17
	v_mfma_f32_16x16x32_bf16 v[52:55], v[52:55], v[18:21], v[32:35]
	s_or_b32 s16, s26, s29
	s_mov_b32 s20, s21
	s_add_u32 s16, s15, s16
	v_lshlrev_b32_e32 v32, 16, v24
	v_and_b32_e32 v33, 0xffff0000, v24
	s_waitcnt lgkmcnt(2)
	v_mfma_f32_16x16x32_bf16 v[40:43], v[36:39], v[4:7], v[40:43]
	v_mul_f32_e64 v32, v26, v32
	v_mul_f32_e64 v33, v26, v33
	v_cvt_pk_bf16_f32 v24, v32, v33
	v_lshlrev_b32_e32 v32, 16, v25
	v_mfma_f32_16x16x32_bf16 v[28:31], v[36:39], v[18:21], v[28:31]
	v_and_b32_e32 v33, 0xffff0000, v25
	v_pk_mul_f32 v[36:37], v[26:27], v[60:61] op_sel_hi:[0,1]
	v_pk_mul_f32 v[26:27], v[26:27], v[32:33] op_sel_hi:[0,1]
	v_cvt_pk_bf16_f32 v23, v36, v37
	v_cvt_pk_bf16_f32 v25, v26, v27
	s_waitcnt lgkmcnt(1)
	v_mfma_f32_16x16x32_bf16 v[86:89], v[44:47], v[0:3], v[40:43]
	v_mov_b64_e32 v[36:37], s[22:23]
	v_readlane_b32 s15, v254, 57
	v_mov_b64_e32 v[64:65], s[22:23]
	s_waitcnt lgkmcnt(0)
	v_mfma_f32_16x16x32_bf16 v[82:85], v[56:59], v[0:3], v[48:51]
	v_mov_b64_e32 v[40:41], s[22:23]
	v_mov_b64_e32 v[68:69], s[22:23]
	v_mov_b64_e32 v[72:73], s[22:23]
	v_mfma_f32_16x16x32_bf16 v[78:81], v[44:47], v[22:25], v[28:31]
	v_mov_b64_e32 v[44:45], s[22:23]
	v_mov_b64_e32 v[48:49], s[22:23]
	v_mov_b64_e32 v[32:33], s[22:23]
	v_mfma_f32_16x16x32_bf16 v[74:77], v[56:59], v[22:25], v[52:55]
	v_mov_b64_e32 v[56:57], s[22:23]
	v_mov_b64_e32 v[60:61], s[22:23]
	v_mov_b64_e32 v[28:29], s[22:23]
	v_mov_b64_e32 v[52:53], s[22:23]
	v_mov_b64_e32 v[34:35], s[20:21]
	s_addc_u32 s17, s15, s27
	v_mov_b64_e32 v[42:43], s[20:21]
	v_mov_b64_e32 v[50:51], s[20:21]
	v_mov_b64_e32 v[54:55], s[20:21]
	v_mov_b64_e32 v[38:39], s[20:21]
	v_mov_b64_e32 v[46:47], s[20:21]
	v_mov_b64_e32 v[58:59], s[20:21]
	v_mov_b64_e32 v[62:63], s[20:21]
	v_mov_b64_e32 v[26:27], s[20:21]
	v_mov_b64_e32 v[30:31], s[20:21]
	v_mov_b64_e32 v[66:67], s[20:21]
	v_mov_b64_e32 v[70:71], s[20:21]
	s_mov_b32 s20, 0
	s_nop 7
	v_mov_b64_e32 v[204:205], v[74:75]
	v_mov_b64_e32 v[206:207], v[76:77]
	v_mov_b64_e32 v[200:201], v[78:79]
	v_mov_b64_e32 v[202:203], v[80:81]
	v_mov_b64_e32 v[196:197], v[82:83]
	v_mov_b64_e32 v[198:199], v[84:85]
	v_mov_b64_e32 v[192:193], v[86:87]
	v_mov_b64_e32 v[194:195], v[88:89]
	s_mov_b32 s29, s28
	s_mov_b32 s30, s28
	s_mov_b32 s31, s28
	v_mov_b64_e32 v[224:225], s[28:29]
	v_mov_b64_e32 v[226:227], s[30:31]
	s_branch .LBB0_650
; __global__ void __launch_bounds__(NTHR, 2) fwd_megakernel(Params P) {
;     ...
;                 auto qkm = [&]() {
; #pragma unroll
;                     for (int t = 0; t < 2; ++t) {
;                         s0[t] = __builtin_amdgcn_mfma_f32_16x16x32_bf16(kf[0], qf[t][0], negm[t], 0, 0, 0);
;                         s1[t] = __builtin_amdgcn_mfma_f32_16x16x32_bf16(kf[1], qf[t][0], negm[t], 0, 0, 0);
;                     }
; #pragma unroll
;                     for (int ks = 1; ks < 3; ++ks)
; #pragma unroll
;                         for (int t = 0; t < 2; ++t) {
;                             s0[t] = __builtin_amdgcn_mfma_f32_16x16x32_bf16(kf[2 * ks], qf[t][ks], s0[t], 0, 0, 0);
;                             s1[t] = __builtin_amdgcn_mfma_f32_16x16x32_bf16(kf[2 * ks + 1], qf[t][ks], s1[t], 0, 0, 0);
;                         }
;                 };
;                 auto smpv = [&](LAS const unsigned char* vp) {
;                     bf16x8 pb[2];
; #pragma unroll
;                     for (int t = 0; t < 2; ++t) {
;                         float mx = __builtin_fmaxf(__builtin_fmaxf(s0[t][0], s0[t][1]), s0[t][2]);
;                         mx = __builtin_fmaxf(__builtin_fmaxf(mx, s0[t][3]), s1[t][0]);
;                         mx = __builtin_fmaxf(__builtin_fmaxf(mx, s1[t][1]), s1[t][2]);
;                         mx = __builtin_fmaxf(mx, s1[t][3]);
;                         if (__any(mx > THR)) {
;                             mx = fmaxf(mx, __shfl_xor(mx, 16)); mx = fmaxf(mx, __shfl_xor(mx, 32));
;                             const float dl = fmaxf(mx, 0.f);
;                             const float alpha = __builtin_amdgcn_exp2f(-dl);
;                             negm[t] = negm[t] - dl;
;                             lacc[t] = lacc[t] * alpha;
; #pragma unroll
;                             for (int db = 0; db < 4; ++db) o[t][db] = o[t][db] * alpha;
;                             s0[t] = s0[t] - dl; s1[t] = s1[t] - dl;
;                         }
;                         u32x4 w;
;                         w.x = pk2(__builtin_amdgcn_exp2f(s0[t][0]), __builtin_amdgcn_exp2f(s0[t][1])); w.y = pk2(__builtin_amdgcn_exp2f(s0[t][2]), __builtin_amdgcn_exp2f(s0[t][3]));
;                         w.z = pk2(__builtin_amdgcn_exp2f(s1[t][0]), __builtin_amdgcn_exp2f(s1[t][1])); w.w = pk2(__builtin_amdgcn_exp2f(s1[t][2]), __builtin_amdgcn_exp2f(s1[t][3]));
.LBB0_649:
	s_waitcnt lgkmcnt(8)
	v_mfma_f32_16x16x32_bf16 v[192:195], v[98:101], v[8:11], v[30:33]
	v_exp_f32_e32 v62, v220
	v_exp_f32_e32 v63, v221
	v_mfma_f32_16x16x32_bf16 v[196:199], v[106:109], v[8:11], v[30:33]
	v_exp_f32_e32 v110, v208
	v_exp_f32_e32 v111, v209
	v_mfma_f32_16x16x32_bf16 v[200:203], v[98:101], v[14:17], v[26:29]
	v_exp_f32_e32 v70, v212
	v_cvt_pk_bf16_f32 v116, v62, v63
	v_mfma_f32_16x16x32_bf16 v[204:207], v[106:109], v[14:17], v[26:29]
	v_exp_f32_e32 v62, v222
	v_exp_f32_e32 v63, v223
	v_cvt_pk_bf16_f32 v110, v110, v111
	v_mfma_f32_16x16x32_bf16 v[192:195], v[86:89], v[4:7], v[192:195]
	v_exp_f32_e32 v111, v210
	v_exp_f32_e32 v112, v211
	v_mfma_f32_16x16x32_bf16 v[196:199], v[102:105], v[4:7], v[196:199]
	v_exp_f32_e32 v71, v213
	v_mfma_f32_16x16x32_bf16 v[200:203], v[86:89], v[18:21], v[200:203]
	v_cvt_pk_bf16_f32 v117, v62, v63
	v_mfma_f32_16x16x32_bf16 v[204:207], v[102:105], v[18:21], v[204:207]
	v_cvt_pk_bf16_f32 v111, v111, v112
	v_mfma_f32_16x16x32_bf16 v[192:195], v[94:97], v[0:3], v[192:195]
	v_cvt_pk_bf16_f32 v112, v70, v71
	v_exp_f32_e32 v70, v214
	v_mfma_f32_16x16x32_bf16 v[196:199], v[90:93], v[0:3], v[196:199]
	v_exp_f32_e32 v71, v215
	v_mfma_f32_16x16x32_bf16 v[200:203], v[94:97], v[22:25], v[200:203]
	v_exp_f32_e32 v66, v216
	v_exp_f32_e32 v67, v217
	v_mfma_f32_16x16x32_bf16 v[204:207], v[90:93], v[22:25], v[204:207]
	v_cvt_pk_bf16_f32 v113, v70, v71
	s_add_i32 s20, s20, 1
	v_cvt_pk_bf16_f32 v114, v66, v67
	v_mfma_f32_16x16x32_bf16 v[70:73], v[224:227], v[110:113], v[50:53]
	v_exp_f32_e32 v66, v218
	v_exp_f32_e32 v67, v219
	s_nop 0
	v_cvt_pk_bf16_f32 v115, v66, v67
	s_nop 1
	v_mfma_f32_16x16x32_bf16 v[66:69], v[224:227], v[114:117], v[58:61]
	s_waitcnt lgkmcnt(0)
	v_mfma_f32_16x16x32_bf16 v[58:61], v[180:183], v[110:113], v[42:45]
	v_mfma_f32_16x16x32_bf16 v[62:65], v[176:179], v[110:113], v[46:49]
	v_mfma_f32_16x16x32_bf16 v[46:49], v[184:187], v[110:113], v[38:41]
	v_mfma_f32_16x16x32_bf16 v[42:45], v[184:187], v[114:117], v[78:81]
	v_mfma_f32_16x16x32_bf16 v[54:57], v[176:179], v[114:117], v[54:57]
	v_mfma_f32_16x16x32_bf16 v[50:53], v[180:183], v[114:117], v[82:85]
	v_mfma_f32_16x16x32_bf16 v[38:41], v[188:191], v[110:113], v[34:37]
	v_mfma_f32_16x16x32_bf16 v[34:37], v[188:191], v[114:117], v[74:77]
	s_add_u32 s0, s0, 0xc0000
	s_addc_u32 s1, s1, 0
	s_add_u32 s16, s16, 0x20000
	s_addc_u32 s17, s17, 0
	s_cmp_eq_u32 s20, 31
	s_cbranch_scc1 .Lmla_exit

; __global__ void __launch_bounds__(NTHR, 2) fwd_megakernel(Params P) {
;     ...
;                 auto qkm = [&]() {
; #pragma unroll
;                     for (int t = 0; t < 2; ++t) {
;                         s0[t] = __builtin_amdgcn_mfma_f32_16x16x32_bf16(kf[0], qf[t][0], negm[t], 0, 0, 0);
;                         s1[t] = __builtin_amdgcn_mfma_f32_16x16x32_bf16(kf[1], qf[t][0], negm[t], 0, 0, 0);
;                     }
; #pragma unroll
;                     for (int ks = 1; ks < 3; ++ks)
; #pragma unroll
;                         for (int t = 0; t < 2; ++t) {
;                             s0[t] = __builtin_amdgcn_mfma_f32_16x16x32_bf16(kf[2 * ks], qf[t][ks], s0[t], 0, 0, 0);
;                             s1[t] = __builtin_amdgcn_mfma_f32_16x16x32_bf16(kf[2 * ks + 1], qf[t][ks], s1[t], 0, 0, 0);
;                         }
;                 };
;                 auto smpv = [&](LAS const unsigned char* vp) {
;                     bf16x8 pb[2];
; #pragma unroll
;                     for (int t = 0; t < 2; ++t) {
;                         float mx = __builtin_fmaxf(__builtin_fmaxf(s0[t][0], s0[t][1]), s0[t][2]);
;                         mx = __builtin_fmaxf(__builtin_fmaxf(mx, s0[t][3]), s1[t][0]);
;                         mx = __builtin_fmaxf(__builtin_fmaxf(mx, s1[t][1]), s1[t][2]);
;                         mx = __builtin_fmaxf(mx, s1[t][3]);
;                         if (__any(mx > THR)) {
;                             mx = fmaxf(mx, __shfl_xor(mx, 16)); mx = fmaxf(mx, __shfl_xor(mx, 32));
;                             const float dl = fmaxf(mx, 0.f);
;                             const float alpha = __builtin_amdgcn_exp2f(-dl);
;                             negm[t] = negm[t] - dl;
;                             lacc[t] = lacc[t] * alpha;
; #pragma unroll
;                             for (int db = 0; db < 4; ++db) o[t][db] = o[t][db] * alpha;
;                             s0[t] = s0[t] - dl; s1[t] = s1[t] - dl;
;                         }
;                         u32x4 w;
;                         w.x = pk2(__builtin_amdgcn_exp2f(s0[t][0]), __builtin_amdgcn_exp2f(s0[t][1])); w.y = pk2(__builtin_amdgcn_exp2f(s0[t][2]), __builtin_amdgcn_exp2f(s0[t][3]));
;                         w.z = pk2(__builtin_amdgcn_exp2f(s1[t][0]), __builtin_amdgcn_exp2f(s1[t][1])); w.w = pk2(__builtin_amdgcn_exp2f(s1[t][2]), __builtin_amdgcn_exp2f(s1[t][3]));
.LBB0_654:
	s_waitcnt lgkmcnt(8)
	v_mfma_f32_16x16x32_bf16 v[208:211], v[102:105], v[8:11], v[30:33]
	v_exp_f32_e32 v78, v200
	v_exp_f32_e32 v79, v201
	v_mfma_f32_16x16x32_bf16 v[212:215], v[110:113], v[8:11], v[30:33]
	v_exp_f32_e32 v74, v204
	v_exp_f32_e32 v75, v205
	v_exp_f32_e32 v86, v192
	v_mfma_f32_16x16x32_bf16 v[216:219], v[102:105], v[14:17], v[26:29]
	v_cvt_pk_bf16_f32 v78, v78, v79
	v_exp_f32_e32 v79, v202
	v_mfma_f32_16x16x32_bf16 v[220:223], v[110:113], v[14:17], v[26:29]
	v_exp_f32_e32 v80, v203
	v_exp_f32_e32 v87, v193
	v_exp_f32_e32 v82, v196
	v_mfma_f32_16x16x32_bf16 v[208:211], v[94:97], v[4:7], v[208:211]
	v_exp_f32_e32 v83, v197
	v_cvt_pk_bf16_f32 v79, v79, v80
	v_mfma_f32_16x16x32_bf16 v[212:215], v[106:109], v[4:7], v[212:215]
	v_cvt_pk_bf16_f32 v80, v74, v75
	v_exp_f32_e32 v74, v206
	v_exp_f32_e32 v75, v207
	v_mfma_f32_16x16x32_bf16 v[216:219], v[94:97], v[18:21], v[216:219]
	v_cvt_pk_bf16_f32 v86, v86, v87
	v_exp_f32_e32 v87, v194
	v_exp_f32_e32 v88, v195
	v_mfma_f32_16x16x32_bf16 v[220:223], v[106:109], v[18:21], v[220:223]
	v_mfma_f32_16x16x32_bf16 v[208:211], v[90:93], v[0:3], v[208:211]
	v_cvt_pk_bf16_f32 v81, v74, v75
	v_mfma_f32_16x16x32_bf16 v[212:215], v[98:101], v[0:3], v[212:215]
	v_cvt_pk_bf16_f32 v87, v87, v88
	v_cvt_pk_bf16_f32 v88, v82, v83
	v_mfma_f32_16x16x32_bf16 v[216:219], v[90:93], v[22:25], v[216:219]
	v_exp_f32_e32 v82, v198
	v_exp_f32_e32 v83, v199
	v_mfma_f32_16x16x32_bf16 v[220:223], v[98:101], v[22:25], v[220:223]
	v_cvt_pk_bf16_f32 v89, v82, v83
	v_mfma_f32_16x16x32_bf16 v[66:69], v[224:227], v[78:81], v[66:69]
	s_nop 0
	v_mfma_f32_16x16x32_bf16 v[70:73], v[224:227], v[86:89], v[70:73]
	s_waitcnt lgkmcnt(0)
	v_mfma_f32_16x16x32_bf16 v[62:65], v[160:163], v[86:89], v[62:65]
	v_mfma_f32_16x16x32_bf16 v[74:77], v[160:163], v[78:81], v[54:57]
	v_mfma_f32_16x16x32_bf16 v[54:57], v[164:167], v[86:89], v[58:61]
	v_mfma_f32_16x16x32_bf16 v[46:49], v[168:171], v[86:89], v[46:49]
	v_mfma_f32_16x16x32_bf16 v[42:45], v[168:171], v[78:81], v[42:45]
	v_mfma_f32_16x16x32_bf16 v[50:53], v[164:167], v[78:81], v[50:53]
	v_mfma_f32_16x16x32_bf16 v[38:41], v[172:175], v[86:89], v[38:41]
	v_mfma_f32_16x16x32_bf16 v[34:37], v[172:175], v[78:81], v[34:37]
	ds_read_b128 v[110:113], v148 offset:14336
	ds_read_b128 v[102:105], v148 offset:14400
	ds_read_b128 v[118:121], v148 offset:17920
	ds_read_b128 v[98:101], v148 offset:14464
	ds_read_b128 v[114:117], v148 offset:17984
	ds_read_b128 v[106:109], v148 offset:18048
	ds_read_b64_tr_b16 v[178:179], v159 offset:36352
	ds_read_b64_tr_b16 v[176:177], v159 offset:33792
	ds_read_b64_tr_b16 v[180:181], v159 offset:33824
	ds_read_b64_tr_b16 v[182:183], v159 offset:36384
	ds_read_b64_tr_b16 v[184:185], v159 offset:33856
	ds_read_b64_tr_b16 v[186:187], v159 offset:36416
	ds_read_b64_tr_b16 v[188:189], v159 offset:33888
	ds_read_b64_tr_b16 v[190:191], v159 offset:36448
	v_max3_f32 v90, v208, v209, v210
	v_max3_f32 v90, v90, v211, v212
	v_max3_f32 v90, v90, v213, v214
	v_max_f32_e32 v90, v90, v215
	v_cmp_lt_f32_e32 vcc, s66, v90
	s_cbranch_vccz .LBB0_656
	v_and_b32_e32 v92, 64, v238
	v_xor_b32_e32 v91, 16, v238
	v_add_u32_e32 v92, 64, v92
	v_cmp_lt_i32_e32 vcc, v91, v92
	s_nop 1
	v_cndmask_b32_e32 v91, v238, v91, vcc
	v_lshlrev_b32_e32 v91, 2, v91
	ds_bpermute_b32 v91, v91, v90
	v_max_f32_e32 v90, v90, v90
	s_waitcnt lgkmcnt(0)
	v_max_f32_e32 v91, v91, v91
	v_max_f32_e32 v90, v90, v91
	v_xor_b32_e32 v91, 32, v238
	v_cmp_lt_i32_e32 vcc, v91, v92
	s_nop 1
	v_cndmask_b32_e32 v91, v238, v91, vcc
	v_lshlrev_b32_e32 v91, 2, v91
	ds_bpermute_b32 v91, v91, v90
	s_waitcnt lgkmcnt(0)
	v_max3_f32 v91, v90, v91, 0
	v_exp_f32_e64 v90, -v91
	v_sub_f32_e32 v33, v33, v91
	v_sub_f32_e32 v32, v32, v91
	v_sub_f32_e32 v31, v31, v91
	v_sub_f32_e32 v30, v30, v91
	v_pk_mul_f32 v[72:73], v[72:73], v[90:91] op_sel_hi:[1,0]
	v_pk_mul_f32 v[70:71], v[70:71], v[90:91] op_sel_hi:[1,0]
	v_pk_mul_f32 v[64:65], v[64:65], v[90:91] op_sel_hi:[1,0]
	v_pk_mul_f32 v[62:63], v[62:63], v[90:91] op_sel_hi:[1,0]
	v_pk_mul_f32 v[56:57], v[90:91], v[56:57] op_sel_hi:[0,1]
	v_pk_mul_f32 v[54:55], v[90:91], v[54:55] op_sel_hi:[0,1]
	v_pk_mul_f32 v[48:49], v[90:91], v[48:49] op_sel_hi:[0,1]
	v_pk_mul_f32 v[46:47], v[90:91], v[46:47] op_sel_hi:[0,1]
	v_pk_mul_f32 v[40:41], v[90:91], v[40:41] op_sel_hi:[0,1]
	v_pk_mul_f32 v[38:39], v[90:91], v[38:39] op_sel_hi:[0,1]
	v_sub_f32_e32 v211, v211, v91
	v_sub_f32_e32 v210, v210, v91
	v_sub_f32_e32 v209, v209, v91
	v_sub_f32_e32 v208, v208, v91
	v_sub_f32_e32 v215, v215, v91
	v_sub_f32_e32 v214, v214, v91
	v_sub_f32_e32 v213, v213, v91
	v_sub_f32_e32 v212, v212, v91

; __global__ void __launch_bounds__(NTHR, 2) fwd_megakernel(Params P) {
;     ...
;                 auto qkm = [&]() {
; #pragma unroll
;                     for (int t = 0; t < 2; ++t) {
;                         s0[t] = __builtin_amdgcn_mfma_f32_16x16x32_bf16(kf[0], qf[t][0], negm[t], 0, 0, 0);
;                         s1[t] = __builtin_amdgcn_mfma_f32_16x16x32_bf16(kf[1], qf[t][0], negm[t], 0, 0, 0);
;                     }
; #pragma unroll
;                     for (int ks = 1; ks < 3; ++ks)
; #pragma unroll
;                         for (int t = 0; t < 2; ++t) {
;                             s0[t] = __builtin_amdgcn_mfma_f32_16x16x32_bf16(kf[2 * ks], qf[t][ks], s0[t], 0, 0, 0);
;                             s1[t] = __builtin_amdgcn_mfma_f32_16x16x32_bf16(kf[2 * ks + 1], qf[t][ks], s1[t], 0, 0, 0);
;                         }
;                 };
;                 auto smpv = [&](LAS const unsigned char* vp) {
;                     bf16x8 pb[2];
; #pragma unroll
;                     for (int t = 0; t < 2; ++t) {
;                         float mx = __builtin_fmaxf(__builtin_fmaxf(s0[t][0], s0[t][1]), s0[t][2]);
;                         mx = __builtin_fmaxf(__builtin_fmaxf(mx, s0[t][3]), s1[t][0]);
;                         mx = __builtin_fmaxf(__builtin_fmaxf(mx, s1[t][1]), s1[t][2]);
;                         mx = __builtin_fmaxf(mx, s1[t][3]);
;                         if (__any(mx > THR)) {
;                             mx = fmaxf(mx, __shfl_xor(mx, 16)); mx = fmaxf(mx, __shfl_xor(mx, 32));
;                             const float dl = fmaxf(mx, 0.f);
;                             const float alpha = __builtin_amdgcn_exp2f(-dl);
;                             negm[t] = negm[t] - dl;
;                             lacc[t] = lacc[t] * alpha;
; #pragma unroll
;                             for (int db = 0; db < 4; ++db) o[t][db] = o[t][db] * alpha;
;                             s0[t] = s0[t] - dl; s1[t] = s1[t] - dl;
;                         }
;                         u32x4 w;
;                         w.x = pk2(__builtin_amdgcn_exp2f(s0[t][0]), __builtin_amdgcn_exp2f(s0[t][1])); w.y = pk2(__builtin_amdgcn_exp2f(s0[t][2]), __builtin_amdgcn_exp2f(s0[t][3]));
;                         w.z = pk2(__builtin_amdgcn_exp2f(s1[t][0]), __builtin_amdgcn_exp2f(s1[t][1])); w.w = pk2(__builtin_amdgcn_exp2f(s1[t][2]), __builtin_amdgcn_exp2f(s1[t][3]));
.LBB0_658:
	s_waitcnt lgkmcnt(8)
	v_mfma_f32_16x16x32_bf16 v[192:195], v[110:113], v[8:11], v[30:33]
	v_exp_f32_e32 v78, v216
	v_exp_f32_e32 v79, v217
	v_mfma_f32_16x16x32_bf16 v[196:199], v[118:121], v[8:11], v[30:33]
	v_exp_f32_e32 v58, v220
	v_exp_f32_e32 v59, v221
	v_mfma_f32_16x16x32_bf16 v[200:203], v[110:113], v[14:17], v[26:29]
	v_exp_f32_e32 v82, v212
	v_cvt_pk_bf16_f32 v154, v78, v79
	v_mfma_f32_16x16x32_bf16 v[204:207], v[118:121], v[14:17], v[26:29]
	v_exp_f32_e32 v78, v218
	v_exp_f32_e32 v79, v219
	v_mfma_f32_16x16x32_bf16 v[192:195], v[102:105], v[4:7], v[192:195]
	v_exp_f32_e32 v83, v213
	v_mfma_f32_16x16x32_bf16 v[196:199], v[114:117], v[4:7], v[196:199]
	v_cvt_pk_bf16_f32 v155, v78, v79
	v_mfma_f32_16x16x32_bf16 v[200:203], v[102:105], v[18:21], v[200:203]
	v_mfma_f32_16x16x32_bf16 v[204:207], v[114:117], v[18:21], v[204:207]
	v_cvt_pk_bf16_f32 v156, v58, v59
	v_exp_f32_e32 v58, v222
	v_mfma_f32_16x16x32_bf16 v[192:195], v[98:101], v[0:3], v[192:195]
	v_exp_f32_e32 v59, v223
	v_mfma_f32_16x16x32_bf16 v[196:199], v[106:109], v[0:3], v[196:199]
	v_cvt_pk_bf16_f32 v152, v82, v83
	v_exp_f32_e32 v82, v214
	v_mfma_f32_16x16x32_bf16 v[200:203], v[98:101], v[22:25], v[200:203]
	v_exp_f32_e32 v83, v215
	v_cvt_pk_bf16_f32 v157, v58, v59
	v_mfma_f32_16x16x32_bf16 v[204:207], v[106:109], v[22:25], v[204:207]
	v_exp_f32_e32 v86, v208
	v_exp_f32_e32 v87, v209
	v_cvt_pk_bf16_f32 v153, v82, v83
	v_mfma_f32_16x16x32_bf16 v[94:97], v[224:227], v[154:157], v[66:69]
	v_cvt_pk_bf16_f32 v150, v86, v87
	v_exp_f32_e32 v86, v210
	v_exp_f32_e32 v87, v211
	s_waitcnt lgkmcnt(0)
	v_mfma_f32_16x16x32_bf16 v[90:93], v[176:179], v[154:157], v[74:77]
	v_cvt_pk_bf16_f32 v151, v86, v87
	s_nop 1
	v_mfma_f32_16x16x32_bf16 v[58:61], v[224:227], v[150:153], v[70:73]
	v_mfma_f32_16x16x32_bf16 v[70:73], v[180:183], v[150:153], v[54:57]
	v_mfma_f32_16x16x32_bf16 v[82:85], v[180:183], v[154:157], v[50:53]
	v_mfma_f32_16x16x32_bf16 v[86:89], v[184:187], v[154:157], v[42:45]
	v_mfma_f32_16x16x32_bf16 v[78:81], v[176:179], v[150:153], v[62:65]
	v_mfma_f32_16x16x32_bf16 v[66:69], v[184:187], v[150:153], v[46:49]
	v_mfma_f32_16x16x32_bf16 v[62:65], v[188:191], v[150:153], v[38:41]
	v_mfma_f32_16x16x32_bf16 v[74:77], v[188:191], v[154:157], v[34:37]
	ds_read_b128 v[110:113], v148 offset:21504
	ds_read_b128 v[102:105], v148 offset:21568
	ds_read_b128 v[118:121], v148 offset:25088
	ds_read_b128 v[98:101], v148 offset:21632
	ds_read_b128 v[114:117], v148 offset:25152
	ds_read_b128 v[106:109], v148 offset:25216
	ds_read_b64_tr_b16 v[162:163], v159 offset:41472
	ds_read_b64_tr_b16 v[160:161], v159 offset:38912
	ds_read_b64_tr_b16 v[164:165], v159 offset:38944
	ds_read_b64_tr_b16 v[166:167], v159 offset:41504
	ds_read_b64_tr_b16 v[168:169], v159 offset:38976
	ds_read_b64_tr_b16 v[170:171], v159 offset:41536
	ds_read_b64_tr_b16 v[172:173], v159 offset:39008
	ds_read_b64_tr_b16 v[174:175], v159 offset:41568
	v_max3_f32 v50, v192, v193, v194
	v_max3_f32 v50, v50, v195, v196
	v_max3_f32 v50, v50, v197, v198
	v_max_f32_e32 v50, v50, v199
	v_cmp_lt_f32_e32 vcc, s66, v50
	s_cbranch_vccz .LBB0_660
	v_and_b32_e32 v52, 64, v238
	v_xor_b32_e32 v51, 16, v238
	v_add_u32_e32 v52, 64, v52
	v_cmp_lt_i32_e32 vcc, v51, v52
	s_nop 1
	v_cndmask_b32_e32 v51, v238, v51, vcc
	v_lshlrev_b32_e32 v51, 2, v51
	ds_bpermute_b32 v51, v51, v50
	v_max_f32_e32 v50, v50, v50
	s_waitcnt lgkmcnt(0)
	v_max_f32_e32 v51, v51, v51
	v_max_f32_e32 v50, v50, v51
	v_xor_b32_e32 v51, 32, v238
	v_cmp_lt_i32_e32 vcc, v51, v52
	s_nop 1
	v_cndmask_b32_e32 v51, v238, v51, vcc
	v_lshlrev_b32_e32 v51, 2, v51
	ds_bpermute_b32 v51, v51, v50
	s_waitcnt lgkmcnt(0)
	v_max3_f32 v51, v50, v51, 0
	v_exp_f32_e64 v50, -v51
	v_sub_f32_e32 v33, v33, v51
	v_sub_f32_e32 v32, v32, v51
	v_sub_f32_e32 v31, v31, v51
	v_sub_f32_e32 v30, v30, v51
	v_pk_mul_f32 v[60:61], v[60:61], v[50:51] op_sel_hi:[1,0]
	v_pk_mul_f32 v[58:59], v[58:59], v[50:51] op_sel_hi:[1,0]
	v_pk_mul_f32 v[80:81], v[80:81], v[50:51] op_sel_hi:[1,0]
	v_pk_mul_f32 v[78:79], v[78:79], v[50:51] op_sel_hi:[1,0]
	v_pk_mul_f32 v[72:73], v[50:51], v[72:73] op_sel_hi:[0,1]
	v_pk_mul_f32 v[70:71], v[50:51], v[70:71] op_sel_hi:[0,1]
	v_pk_mul_f32 v[68:69], v[50:51], v[68:69] op_sel_hi:[0,1]
	v_pk_mul_f32 v[66:67], v[50:51], v[66:67] op_sel_hi:[0,1]
	v_pk_mul_f32 v[64:65], v[50:51], v[64:65] op_sel_hi:[0,1]
	v_pk_mul_f32 v[62:63], v[50:51], v[62:63] op_sel_hi:[0,1]
	v_sub_f32_e32 v195, v195, v51
	v_sub_f32_e32 v194, v194, v51
	v_sub_f32_e32 v193, v193, v51
	v_sub_f32_e32 v192, v192, v51
	v_sub_f32_e32 v199, v199, v51
	v_sub_f32_e32 v198, v198, v51
	v_sub_f32_e32 v197, v197, v51
	v_sub_f32_e32 v196, v196, v51

; __global__ void __launch_bounds__(NTHR, 2) fwd_megakernel(Params P) {
;     ...
;                 auto qkm = [&]() {
; #pragma unroll
;                     for (int t = 0; t < 2; ++t) {
;                         s0[t] = __builtin_amdgcn_mfma_f32_16x16x32_bf16(kf[0], qf[t][0], negm[t], 0, 0, 0);
;                         s1[t] = __builtin_amdgcn_mfma_f32_16x16x32_bf16(kf[1], qf[t][0], negm[t], 0, 0, 0);
;                     }
; #pragma unroll
;                     for (int ks = 1; ks < 3; ++ks)
; #pragma unroll
;                         for (int t = 0; t < 2; ++t) {
;                             s0[t] = __builtin_amdgcn_mfma_f32_16x16x32_bf16(kf[2 * ks], qf[t][ks], s0[t], 0, 0, 0);
;                             s1[t] = __builtin_amdgcn_mfma_f32_16x16x32_bf16(kf[2 * ks + 1], qf[t][ks], s1[t], 0, 0, 0);
;                         }
;                 };
;                 auto smpv = [&](LAS const unsigned char* vp) {
;                     bf16x8 pb[2];
; #pragma unroll
;                     for (int t = 0; t < 2; ++t) {
;                         float mx = __builtin_fmaxf(__builtin_fmaxf(s0[t][0], s0[t][1]), s0[t][2]);
;                         mx = __builtin_fmaxf(__builtin_fmaxf(mx, s0[t][3]), s1[t][0]);
;                         mx = __builtin_fmaxf(__builtin_fmaxf(mx, s1[t][1]), s1[t][2]);
;                         mx = __builtin_fmaxf(mx, s1[t][3]);
;                         if (__any(mx > THR)) {
;                             mx = fmaxf(mx, __shfl_xor(mx, 16)); mx = fmaxf(mx, __shfl_xor(mx, 32));
;                             const float dl = fmaxf(mx, 0.f);
;                             const float alpha = __builtin_amdgcn_exp2f(-dl);
;                             negm[t] = negm[t] - dl;
;                             lacc[t] = lacc[t] * alpha;
; #pragma unroll
;                             for (int db = 0; db < 4; ++db) o[t][db] = o[t][db] * alpha;
;                             s0[t] = s0[t] - dl; s1[t] = s1[t] - dl;
;                         }
;                         u32x4 w;
;                         w.x = pk2(__builtin_amdgcn_exp2f(s0[t][0]), __builtin_amdgcn_exp2f(s0[t][1])); w.y = pk2(__builtin_amdgcn_exp2f(s0[t][2]), __builtin_amdgcn_exp2f(s0[t][3]));
;                         w.z = pk2(__builtin_amdgcn_exp2f(s1[t][0]), __builtin_amdgcn_exp2f(s1[t][1])); w.w = pk2(__builtin_amdgcn_exp2f(s1[t][2]), __builtin_amdgcn_exp2f(s1[t][3]));
.LBB0_662:
	s_waitcnt lgkmcnt(8)
	v_mfma_f32_16x16x32_bf16 v[208:211], v[110:113], v[8:11], v[30:33]
	v_exp_f32_e32 v34, v204
	v_exp_f32_e32 v35, v205
	v_mfma_f32_16x16x32_bf16 v[212:215], v[118:121], v[8:11], v[30:33]
	v_exp_f32_e32 v46, v192
	v_exp_f32_e32 v47, v193
	v_exp_f32_e32 v42, v196
	v_mfma_f32_16x16x32_bf16 v[216:219], v[110:113], v[14:17], v[26:29]
	v_cvt_pk_bf16_f32 v154, v34, v35
	v_exp_f32_e32 v34, v206
	v_mfma_f32_16x16x32_bf16 v[220:223], v[118:121], v[14:17], v[26:29]
	v_exp_f32_e32 v35, v207
	v_exp_f32_e32 v43, v197
	v_exp_f32_e32 v38, v200
	v_mfma_f32_16x16x32_bf16 v[208:211], v[102:105], v[4:7], v[208:211]
	v_exp_f32_e32 v39, v201
	v_mfma_f32_16x16x32_bf16 v[212:215], v[114:117], v[4:7], v[212:215]
	v_cvt_pk_bf16_f32 v155, v34, v35
	v_mfma_f32_16x16x32_bf16 v[216:219], v[102:105], v[18:21], v[216:219]
	v_cvt_pk_bf16_f32 v148, v46, v47
	v_mfma_f32_16x16x32_bf16 v[220:223], v[114:117], v[18:21], v[220:223]
	v_exp_f32_e32 v46, v194
	v_exp_f32_e32 v47, v195
	v_cvt_pk_bf16_f32 v150, v42, v43
	v_mfma_f32_16x16x32_bf16 v[208:211], v[98:101], v[0:3], v[208:211]
	v_exp_f32_e32 v42, v198
	v_exp_f32_e32 v43, v199
	v_mfma_f32_16x16x32_bf16 v[212:215], v[106:109], v[0:3], v[212:215]
	v_cvt_pk_bf16_f32 v152, v38, v39
	v_exp_f32_e32 v38, v202
	v_exp_f32_e32 v39, v203
	v_mfma_f32_16x16x32_bf16 v[216:219], v[98:101], v[22:25], v[216:219]
	v_cvt_pk_bf16_f32 v149, v46, v47
	v_mfma_f32_16x16x32_bf16 v[220:223], v[106:109], v[22:25], v[220:223]
	v_cvt_pk_bf16_f32 v151, v42, v43
	v_cvt_pk_bf16_f32 v153, v38, v39
	s_nop 0
	v_mfma_f32_16x16x32_bf16 v[50:53], v[224:227], v[148:151], v[58:61]
	v_mfma_f32_16x16x32_bf16 v[58:61], v[224:227], v[152:155], v[94:97]
	s_waitcnt lgkmcnt(0)
	v_mfma_f32_16x16x32_bf16 v[46:49], v[160:163], v[148:151], v[78:81]
	v_mfma_f32_16x16x32_bf16 v[54:57], v[160:163], v[152:155], v[90:93]
	v_mfma_f32_16x16x32_bf16 v[42:45], v[164:167], v[148:151], v[70:73]
	v_mfma_f32_16x16x32_bf16 v[82:85], v[164:167], v[152:155], v[82:85]
	v_mfma_f32_16x16x32_bf16 v[38:41], v[168:171], v[148:151], v[66:69]
	v_mfma_f32_16x16x32_bf16 v[78:81], v[168:171], v[152:155], v[86:89]
	v_mfma_f32_16x16x32_bf16 v[34:37], v[172:175], v[148:151], v[62:65]
	v_mfma_f32_16x16x32_bf16 v[74:77], v[172:175], v[152:155], v[74:77]
	s_waitcnt vmcnt(0)
	s_cmp_gt_u32 s20, 29
	s_barrier
	s_cbranch_scc1 .LBB0_664
	s_add_i32 s22, s22, 0xffff4000
	s_cmp_lg_u32 s36, 0
	s_cselect_b32 s22, s22, 0x18000
	v_mov_b32_e32 v88, s1
	v_mov_b32_e32 v89, s17
	v_mov_b32_e32 v90, s0
	v_mov_b32_e32 v91, s16
	v_cndmask_b32_e64 v87, v88, v89, s[2:3]
	v_cndmask_b32_e64 v86, v90, v91, s[2:3]
	s_add_i32 s22, s18, s22
	v_lshl_add_u64 v[86:87], v[86:87], 0, v[128:129]
	s_mov_b32 m0, s22
	s_nop 0
	global_load_lds_dwordx4 v[86:87], off
	v_cndmask_b32_e64 v87, v88, v89, s[4:5]
	v_cndmask_b32_e64 v86, v90, v91, s[4:5]
	v_lshl_add_u64 v[86:87], v[86:87], 0, v[130:131]
	s_add_i32 m0, s22, 0x2000
	s_nop 0
	global_load_lds_dwordx4 v[86:87], off
	v_cndmask_b32_e64 v87, v88, v89, s[6:7]
	v_cndmask_b32_e64 v86, v90, v91, s[6:7]
	v_lshl_add_u64 v[86:87], v[86:87], 0, v[132:133]
	s_add_i32 m0, s22, 0x4000
	s_nop 0
	global_load_lds_dwordx4 v[86:87], off
	v_cndmask_b32_e64 v87, v88, v89, s[8:9]
	v_cndmask_b32_e64 v86, v90, v91, s[8:9]
	v_lshl_add_u64 v[86:87], v[86:87], 0, v[134:135]
	s_add_i32 m0, s22, 0x6000
	s_nop 0
	global_load_lds_dwordx4 v[86:87], off
	v_cndmask_b32_e64 v87, v88, v89, s[10:11]
	v_cndmask_b32_e64 v86, v90, v91, s[10:11]
	v_lshl_add_u64 v[86:87], v[86:87], 0, v[136:137]
	s_add_i32 m0, s22, 0x8000
	s_nop 0
	global_load_lds_dwordx4 v[86:87], off
	v_cndmask_b32_e64 v87, v88, v89, s[12:13]
	v_cndmask_b32_e64 v86, v90, v91, s[12:13]
	v_lshl_add_u64 v[86:87], v[86:87], 0, v[138:139]
	s_add_i32 m0, s22, 0xa000
	s_nop 0
	global_load_lds_dwordx4 v[86:87], off

; #define LAS __attribute__((address_space(3)))
;     __device__ __forceinline__ void operator()(f32x4 (&acc)[2][2][4][2], const Unit& u, int wr, int wc, int fr, int fq) const {
;         const LAS float* S = (const LAS float*)(xl + 4096);
;         const float* md = modb + (size_t)(u.pm >> 4) * 6144;
;         rowstat(acc, u, wr, wc, fr, fq, slot1, cnt1);
; #pragma unroll
;         for (int bj = 0; bj < 2; ++bj)
; #pragma unroll
;             for (int n = 0; n < 2; ++n) {
;                 const int col = u.pn * BM + bj * HALF + wc * 32 + 8 * fq + 4 * n;
;                 const f32x4 gg = *(const f32x4*)(md + gate_off + col) * *(const f32x4*)(gpost + col);
; #pragma unroll
;                 for (int ai = 0; ai < 2; ++ai)
; #pragma unroll
;                     for (int m = 0; m < 4; ++m) {
;                         const int rl = ai * HALF + wr * 64 + m * 16 + fr; const size_t off = (size_t)(u.pm * BM + rl) * DM + col;
;                         const f32x4 xv = *(const f32x4*)(xin + off);
;                         const f32x4 xn = xv + gg * (acc[ai][bj][m][n] * S[rl]);
.LBB0_1220:
	s_or_b64 exec, exec, s[8:9]
	s_ashr_i32 s8, s96, 4
	s_mul_hi_i32 s9, s8, 0x6000
	s_mulk_i32 s8, 0x6000
	s_add_u32 s49, s25, s8
	s_addc_u32 s50, s29, s9
	v_lshl_or_b32 v184, s82, 8, v221
	s_lshl_b32 s8, s96, 8
	s_add_u32 vcc_lo, s49, 0x5000
	v_ashrrev_i32_e32 v185, 31, v184
	s_addc_u32 vcc_hi, s50, 0
	v_lshlrev_b64 v[194:195], 2, v[184:185]
	s_waitcnt vmcnt(0) lgkmcnt(0)
	s_barrier
	s_waitcnt lgkmcnt(0)
	v_lshl_add_u64 v[196:197], vcc, 0, v[194:195]
	v_lshl_add_u64 v[198:199], s[16:17], 0, v[194:195]
	global_load_dwordx4 v[130:133], v[196:197], off
	global_load_dwordx4 v[134:137], v[198:199], off
	v_add_u32_e32 v204, s8, v205
	v_add_u32_e32 v208, s8, v241
	v_add_u32_e32 v220, s8, v229
	v_add_u32_e32 v222, s8, v231
	v_add_u32_e32 v228, s8, v240
	v_add_u32_e32 v230, s8, v242
	v_add_u32_e32 v171, s8, v243
	v_add_u32_e32 v176, s8, v244
	v_lshl_add_u32 v204, v204, 10, v184
	v_lshl_add_u32 v208, v208, 10, v184
	v_lshl_add_u32 v220, v220, 10, v184
	v_lshl_add_u32 v222, v222, 10, v184
	v_lshl_add_u32 v228, v228, 10, v184
	v_lshl_add_u32 v230, v230, 10, v184
	v_lshl_add_u32 v171, v171, 10, v184
	v_lshl_add_u32 v176, v176, 10, v184
	v_lshlrev_b32_e32 v204, 2, v204
	v_lshlrev_b32_e32 v208, 2, v208
	v_lshlrev_b32_e32 v220, 2, v220
	v_lshlrev_b32_e32 v222, 2, v222
	v_lshlrev_b32_e32 v228, 2, v228
	v_lshlrev_b32_e32 v230, 2, v230
	v_lshlrev_b32_e32 v171, 2, v171
	v_lshlrev_b32_e32 v176, 2, v176
	global_load_dwordx4 v[138:141], v204, s[60:61]
	global_load_dwordx4 v[142:145], v208, s[60:61]
	global_load_dwordx4 v[146:149], v220, s[60:61]
	global_load_dwordx4 v[172:175], v222, s[60:61]
	global_load_dwordx4 v[200:203], v228, s[60:61]
	global_load_dwordx4 v[210:213], v230, s[60:61]
	global_load_dwordx4 v[214:217], v171, s[60:61]
	global_load_dwordx4 v[224:227], v176, s[60:61]
	ds_read_b32 v164, v246
	ds_read_b32 v178, v247
	ds_read_b32 v180, v248
	ds_read_b32 v182, v249
	ds_read_b32 v190, v250
	ds_read_b32 v192, v251
	ds_read_b32 v206, v236
	ds_read_b32 v218, v166
	s_waitcnt lgkmcnt(7)
	v_pk_mul_f32 v[78:79], v[78:79], v[164:165] op_sel_hi:[1,0]
	v_pk_mul_f32 v[80:81], v[80:81], v[164:165] op_sel_hi:[1,0]
	v_pk_mul_f32 v[106:107], v[106:107], v[164:165] op_sel_hi:[1,0]
	v_pk_mul_f32 v[108:109], v[108:109], v[164:165] op_sel_hi:[1,0]
	v_pk_mul_f32 v[102:103], v[102:103], v[164:165] op_sel_hi:[1,0]
	v_pk_mul_f32 v[104:105], v[104:105], v[164:165] op_sel_hi:[1,0]
	v_pk_mul_f32 v[34:35], v[34:35], v[164:165] op_sel_hi:[1,0]
	v_pk_mul_f32 v[36:37], v[36:37], v[164:165] op_sel_hi:[1,0]
	s_waitcnt lgkmcnt(6)
	v_pk_mul_f32 v[74:75], v[74:75], v[178:179] op_sel_hi:[1,0]
	v_pk_mul_f32 v[76:77], v[76:77], v[178:179] op_sel_hi:[1,0]
	v_pk_mul_f32 v[98:99], v[98:99], v[178:179] op_sel_hi:[1,0]
	v_pk_mul_f32 v[100:101], v[100:101], v[178:179] op_sel_hi:[1,0]
	v_pk_mul_f32 v[94:95], v[94:95], v[178:179] op_sel_hi:[1,0]
	v_pk_mul_f32 v[96:97], v[96:97], v[178:179] op_sel_hi:[1,0]
	v_pk_mul_f32 v[30:31], v[30:31], v[178:179] op_sel_hi:[1,0]
	v_pk_mul_f32 v[32:33], v[32:33], v[178:179] op_sel_hi:[1,0]
	s_waitcnt lgkmcnt(5)
	v_pk_mul_f32 v[70:71], v[70:71], v[180:181] op_sel_hi:[1,0]
	v_pk_mul_f32 v[72:73], v[72:73], v[180:181] op_sel_hi:[1,0]
	v_pk_mul_f32 v[86:87], v[86:87], v[180:181] op_sel_hi:[1,0]
	v_pk_mul_f32 v[88:89], v[88:89], v[180:181] op_sel_hi:[1,0]
	v_pk_mul_f32 v[90:91], v[90:91], v[180:181] op_sel_hi:[1,0]
	v_pk_mul_f32 v[92:93], v[92:93], v[180:181] op_sel_hi:[1,0]
	v_pk_mul_f32 v[26:27], v[26:27], v[180:181] op_sel_hi:[1,0]
	v_pk_mul_f32 v[28:29], v[28:29], v[180:181] op_sel_hi:[1,0]
	s_waitcnt lgkmcnt(4)
	v_pk_mul_f32 v[62:63], v[62:63], v[182:183] op_sel_hi:[1,0]
	v_pk_mul_f32 v[64:65], v[64:65], v[182:183] op_sel_hi:[1,0]
	v_pk_mul_f32 v[122:123], v[122:123], v[182:183] op_sel_hi:[1,0]
	v_pk_mul_f32 v[124:125], v[124:125], v[182:183] op_sel_hi:[1,0]
	v_pk_mul_f32 v[82:83], v[82:83], v[182:183] op_sel_hi:[1,0]
	v_pk_mul_f32 v[84:85], v[84:85], v[182:183] op_sel_hi:[1,0]
	v_pk_mul_f32 v[22:23], v[22:23], v[182:183] op_sel_hi:[1,0]
	v_pk_mul_f32 v[24:25], v[24:25], v[182:183] op_sel_hi:[1,0]
	s_waitcnt lgkmcnt(3)
	v_pk_mul_f32 v[58:59], v[58:59], v[190:191] op_sel_hi:[1,0]
	v_pk_mul_f32 v[60:61], v[60:61], v[190:191] op_sel_hi:[1,0]
	v_pk_mul_f32 v[118:119], v[118:119], v[190:191] op_sel_hi:[1,0]
	v_pk_mul_f32 v[120:121], v[120:121], v[190:191] op_sel_hi:[1,0]
	v_pk_mul_f32 v[66:67], v[66:67], v[190:191] op_sel_hi:[1,0]
	v_pk_mul_f32 v[68:69], v[68:69], v[190:191] op_sel_hi:[1,0]
	v_pk_mul_f32 v[14:15], v[14:15], v[190:191] op_sel_hi:[1,0]
	v_pk_mul_f32 v[16:17], v[16:17], v[190:191] op_sel_hi:[1,0]
	s_waitcnt lgkmcnt(2)
	v_pk_mul_f32 v[54:55], v[54:55], v[192:193] op_sel_hi:[1,0]
	v_pk_mul_f32 v[56:57], v[56:57], v[192:193] op_sel_hi:[1,0]
	v_pk_mul_f32 v[126:127], v[126:127], v[192:193] op_sel_hi:[1,0]
	v_pk_mul_f32 v[128:129], v[128:129], v[192:193] op_sel_hi:[1,0]
	v_pk_mul_f32 v[42:43], v[42:43], v[192:193] op_sel_hi:[1,0]
	v_pk_mul_f32 v[44:45], v[44:45], v[192:193] op_sel_hi:[1,0]
	v_pk_mul_f32 v[8:9], v[8:9], v[192:193] op_sel_hi:[1,0]
	v_pk_mul_f32 v[10:11], v[10:11], v[192:193] op_sel_hi:[1,0]
	s_waitcnt lgkmcnt(1)
	v_pk_mul_f32 v[50:51], v[50:51], v[206:207] op_sel_hi:[1,0]
	v_pk_mul_f32 v[52:53], v[52:53], v[206:207] op_sel_hi:[1,0]
	v_pk_mul_f32 v[114:115], v[114:115], v[206:207] op_sel_hi:[1,0]
	v_pk_mul_f32 v[116:117], v[116:117], v[206:207] op_sel_hi:[1,0]
	v_pk_mul_f32 v[38:39], v[38:39], v[206:207] op_sel_hi:[1,0]
	v_pk_mul_f32 v[40:41], v[40:41], v[206:207] op_sel_hi:[1,0]
	v_pk_mul_f32 v[4:5], v[4:5], v[206:207] op_sel_hi:[1,0]
	v_pk_mul_f32 v[6:7], v[6:7], v[206:207] op_sel_hi:[1,0]
	s_waitcnt lgkmcnt(0)
;     __device__ __forceinline__ void operator()(f32x4 (&acc)[2][2][4][2], const Unit& u, int wr, int wc, int fr, int fq) const {
;     ...
;             for (int n = 0; n < 2; ++n) {
;                 const int col = u.pn * BM + bj * HALF + wc * 32 + 8 * fq + 4 * n;
;                 const f32x4 gg = *(const f32x4*)(md + gate_off + col) * *(const f32x4*)(gpost + col);
; #pragma unroll
;                 for (int ai = 0; ai < 2; ++ai)
; #pragma unroll
;                     for (int m = 0; m < 4; ++m) {
;                         const int rl = ai * HALF + wr * 64 + m * 16 + fr; const size_t off = (size_t)(u.pm * BM + rl) * DM + col;
;                         const f32x4 xv = *(const f32x4*)(xin + off);
;                         const f32x4 xn = xv + gg * (acc[ai][bj][m][n] * S[rl]);
;                         acc[ai][bj][m][n] = xn; *(f32x4*)(xout + off) = xn;
;                     }
	v_pk_mul_f32 v[46:47], v[46:47], v[218:219] op_sel_hi:[1,0]
	v_pk_mul_f32 v[48:49], v[48:49], v[218:219] op_sel_hi:[1,0]
	v_pk_mul_f32 v[110:111], v[110:111], v[218:219] op_sel_hi:[1,0]
	v_pk_mul_f32 v[112:113], v[112:113], v[218:219] op_sel_hi:[1,0]
	v_pk_mul_f32 v[18:19], v[18:19], v[218:219] op_sel_hi:[1,0]
	v_pk_mul_f32 v[20:21], v[20:21], v[218:219] op_sel_hi:[1,0]
	v_pk_mul_f32 v[0:1], v[0:1], v[218:219] op_sel_hi:[1,0]
	v_pk_mul_f32 v[2:3], v[2:3], v[218:219] op_sel_hi:[1,0]
	s_waitcnt vmcnt(8)
	v_pk_mul_f32 v[232:233], v[130:131], v[134:135]
	v_pk_mul_f32 v[234:235], v[132:133], v[136:137]
	global_load_dwordx4 v[130:133], v[196:197], off offset:16
	global_load_dwordx4 v[134:137], v[198:199], off offset:16
	s_waitcnt vmcnt(9)
	v_pk_fma_f32 v[80:81], v[234:235], v[80:81], v[140:141]
	v_pk_fma_f32 v[78:79], v[232:233], v[78:79], v[138:139]
	global_store_dwordx4 v204, v[78:81], s[60:61]
	global_load_dwordx4 v[138:141], v204, s[60:61] offset:16
	s_waitcnt vmcnt(10)
	v_pk_fma_f32 v[76:77], v[234:235], v[76:77], v[144:145]
	v_pk_fma_f32 v[74:75], v[232:233], v[74:75], v[142:143]
	global_store_dwordx4 v208, v[74:77], s[60:61]
	global_load_dwordx4 v[142:145], v208, s[60:61] offset:16
	s_waitcnt vmcnt(11)
	v_pk_fma_f32 v[72:73], v[234:235], v[72:73], v[148:149]
	v_pk_fma_f32 v[70:71], v[232:233], v[70:71], v[146:147]
	global_store_dwordx4 v220, v[70:73], s[60:61]
	global_load_dwordx4 v[146:149], v220, s[60:61] offset:16
	s_waitcnt vmcnt(12)
	v_pk_fma_f32 v[64:65], v[234:235], v[64:65], v[174:175]
	v_pk_fma_f32 v[62:63], v[232:233], v[62:63], v[172:173]
	global_store_dwordx4 v222, v[62:65], s[60:61]
	global_load_dwordx4 v[172:175], v222, s[60:61] offset:16
	s_waitcnt vmcnt(13)
	v_pk_fma_f32 v[60:61], v[234:235], v[60:61], v[202:203]
	v_pk_fma_f32 v[58:59], v[232:233], v[58:59], v[200:201]
	global_store_dwordx4 v228, v[58:61], s[60:61]
	global_load_dwordx4 v[200:203], v228, s[60:61] offset:16
	s_waitcnt vmcnt(14)
	v_pk_fma_f32 v[56:57], v[234:235], v[56:57], v[212:213]
	v_pk_fma_f32 v[54:55], v[232:233], v[54:55], v[210:211]
	global_store_dwordx4 v230, v[54:57], s[60:61]
	global_load_dwordx4 v[210:213], v230, s[60:61] offset:16
	s_waitcnt vmcnt(15)
	v_pk_fma_f32 v[52:53], v[234:235], v[52:53], v[216:217]
	v_pk_fma_f32 v[50:51], v[232:233], v[50:51], v[214:215]
	global_store_dwordx4 v171, v[50:53], s[60:61]
	global_load_dwordx4 v[214:217], v171, s[60:61] offset:16
	s_waitcnt vmcnt(16)
	v_pk_fma_f32 v[48:49], v[234:235], v[48:49], v[226:227]
	v_pk_fma_f32 v[46:47], v[232:233], v[46:47], v[224:225]
	global_store_dwordx4 v176, v[46:49], s[60:61]
	global_load_dwordx4 v[224:227], v176, s[60:61] offset:16
	s_waitcnt vmcnt(16)
	v_pk_mul_f32 v[186:187], v[130:131], v[134:135]
	v_pk_mul_f32 v[188:189], v[132:133], v[136:137]
	global_load_dwordx4 v[130:133], v[196:197], off offset:512
	global_load_dwordx4 v[134:137], v[198:199], off offset:512
	s_waitcnt vmcnt(16)
	v_pk_fma_f32 v[108:109], v[188:189], v[108:109], v[140:141]
	v_pk_fma_f32 v[106:107], v[186:187], v[106:107], v[138:139]
	global_store_dwordx4 v204, v[106:109], s[60:61] offset:16
	global_load_dwordx4 v[138:141], v204, s[60:61] offset:512
	s_waitcnt vmcnt(16)
	v_pk_fma_f32 v[100:101], v[188:189], v[100:101], v[144:145]
	v_pk_fma_f32 v[98:99], v[186:187], v[98:99], v[142:143]
	global_store_dwordx4 v208, v[98:101], s[60:61] offset:16
	global_load_dwordx4 v[142:145], v208, s[60:61] offset:512
	s_waitcnt vmcnt(16)
	v_pk_fma_f32 v[88:89], v[188:189], v[88:89], v[148:149]
	v_pk_fma_f32 v[86:87], v[186:187], v[86:87], v[146:147]
	global_store_dwordx4 v220, v[86:89], s[60:61] offset:16
	global_load_dwordx4 v[146:149], v220, s[60:61] offset:512
	s_waitcnt vmcnt(16)
	v_pk_fma_f32 v[124:125], v[188:189], v[124:125], v[174:175]
	v_pk_fma_f32 v[122:123], v[186:187], v[122:123], v[172:173]
	global_store_dwordx4 v222, v[122:125], s[60:61] offset:16
	global_load_dwordx4 v[172:175], v222, s[60:61] offset:512
	s_waitcnt vmcnt(16)
	v_pk_fma_f32 v[120:121], v[188:189], v[120:121], v[202:203]
	v_pk_fma_f32 v[118:119], v[186:187], v[118:119], v[200:201]
	global_store_dwordx4 v228, v[118:121], s[60:61] offset:16
	global_load_dwordx4 v[200:203], v228, s[60:61] offset:512
	s_waitcnt vmcnt(16)
	v_pk_fma_f32 v[128:129], v[188:189], v[128:129], v[212:213]
	v_pk_fma_f32 v[126:127], v[186:187], v[126:127], v[210:211]
	global_store_dwordx4 v230, v[126:129], s[60:61] offset:16
	global_load_dwordx4 v[210:213], v230, s[60:61] offset:512
	s_waitcnt vmcnt(16)
	v_pk_fma_f32 v[116:117], v[188:189], v[116:117], v[216:217]
	v_pk_fma_f32 v[114:115], v[186:187], v[114:115], v[214:215]
	global_store_dwordx4 v171, v[114:117], s[60:61] offset:16
	global_load_dwordx4 v[214:217], v171, s[60:61] offset:512
	s_waitcnt vmcnt(16)
	v_pk_fma_f32 v[112:113], v[188:189], v[112:113], v[226:227]
	v_pk_fma_f32 v[110:111], v[186:187], v[110:111], v[224:225]
	global_store_dwordx4 v176, v[110:113], s[60:61] offset:16
	global_load_dwordx4 v[224:227], v176, s[60:61] offset:512
	s_waitcnt vmcnt(16)
	v_pk_mul_f32 v[232:233], v[130:131], v[134:135]
	v_pk_mul_f32 v[234:235], v[132:133], v[136:137]
	global_load_dwordx4 v[130:133], v[196:197], off offset:528
	global_load_dwordx4 v[134:137], v[198:199], off offset:528
	s_waitcnt vmcnt(16)
;     __device__ __forceinline__ void operator()(f32x4 (&acc)[2][2][4][2], const Unit& u, int wr, int wc, int fr, int fq) const {
;     ...
;             for (int n = 0; n < 2; ++n) {
;                 const int col = u.pn * BM + bj * HALF + wc * 32 + 8 * fq + 4 * n;
;                 const f32x4 gg = *(const f32x4*)(md + gate_off + col) * *(const f32x4*)(gpost + col);
; #pragma unroll
;                 for (int ai = 0; ai < 2; ++ai)
; #pragma unroll
;                     for (int m = 0; m < 4; ++m) {
;                         const int rl = ai * HALF + wr * 64 + m * 16 + fr; const size_t off = (size_t)(u.pm * BM + rl) * DM + col;
;                         const f32x4 xv = *(const f32x4*)(xin + off);
;                         const f32x4 xn = xv + gg * (acc[ai][bj][m][n] * S[rl]);
;                         acc[ai][bj][m][n] = xn; *(f32x4*)(xout + off) = xn;
;                     }
;             }
;         if (XN == nullptr) return;
;         asm volatile("s_waitcnt lgkmcnt(0)" ::: "memory"); __builtin_amdgcn_s_barrier(); asm volatile("" ::: "memory");
;         rowstat(acc, u, wr, wc, fr, fq, slot2, cnt2);
	v_pk_fma_f32 v[104:105], v[234:235], v[104:105], v[140:141]
	v_pk_fma_f32 v[102:103], v[232:233], v[102:103], v[138:139]
	global_store_dwordx4 v204, v[102:105], s[60:61] offset:512
	global_load_dwordx4 v[138:141], v204, s[60:61] offset:528
	s_waitcnt vmcnt(16)
	v_pk_fma_f32 v[96:97], v[234:235], v[96:97], v[144:145]
	v_pk_fma_f32 v[94:95], v[232:233], v[94:95], v[142:143]
	global_store_dwordx4 v208, v[94:97], s[60:61] offset:512
	global_load_dwordx4 v[142:145], v208, s[60:61] offset:528
	s_waitcnt vmcnt(16)
	v_pk_fma_f32 v[92:93], v[234:235], v[92:93], v[148:149]
	v_pk_fma_f32 v[90:91], v[232:233], v[90:91], v[146:147]
	global_store_dwordx4 v220, v[90:93], s[60:61] offset:512
	global_load_dwordx4 v[146:149], v220, s[60:61] offset:528
	s_waitcnt vmcnt(16)
	v_pk_fma_f32 v[84:85], v[234:235], v[84:85], v[174:175]
	v_pk_fma_f32 v[82:83], v[232:233], v[82:83], v[172:173]
	global_store_dwordx4 v222, v[82:85], s[60:61] offset:512
	global_load_dwordx4 v[172:175], v222, s[60:61] offset:528
	s_waitcnt vmcnt(16)
	v_pk_fma_f32 v[68:69], v[234:235], v[68:69], v[202:203]
	v_pk_fma_f32 v[66:67], v[232:233], v[66:67], v[200:201]
	global_store_dwordx4 v228, v[66:69], s[60:61] offset:512
	global_load_dwordx4 v[200:203], v228, s[60:61] offset:528
	s_waitcnt vmcnt(16)
	v_pk_fma_f32 v[44:45], v[234:235], v[44:45], v[212:213]
	v_pk_fma_f32 v[42:43], v[232:233], v[42:43], v[210:211]
	global_store_dwordx4 v230, v[42:45], s[60:61] offset:512
	global_load_dwordx4 v[210:213], v230, s[60:61] offset:528
	s_waitcnt vmcnt(16)
	v_pk_fma_f32 v[40:41], v[234:235], v[40:41], v[216:217]
	v_pk_fma_f32 v[38:39], v[232:233], v[38:39], v[214:215]
	global_store_dwordx4 v171, v[38:41], s[60:61] offset:512
	global_load_dwordx4 v[214:217], v171, s[60:61] offset:528
	s_waitcnt vmcnt(16)
	v_pk_fma_f32 v[20:21], v[234:235], v[20:21], v[226:227]
	v_pk_fma_f32 v[18:19], v[232:233], v[18:19], v[224:225]
	global_store_dwordx4 v176, v[18:21], s[60:61] offset:512
	global_load_dwordx4 v[224:227], v176, s[60:61] offset:528
	s_waitcnt vmcnt(16)
	v_pk_mul_f32 v[186:187], v[130:131], v[134:135]
	v_pk_mul_f32 v[188:189], v[132:133], v[136:137]
	s_waitcnt vmcnt(14)
	v_pk_fma_f32 v[36:37], v[188:189], v[36:37], v[140:141]
	v_pk_fma_f32 v[34:35], v[186:187], v[34:35], v[138:139]
	global_store_dwordx4 v204, v[34:37], s[60:61] offset:528
	s_waitcnt vmcnt(13)
	v_pk_fma_f32 v[132:133], v[188:189], v[32:33], v[144:145]
	v_pk_fma_f32 v[130:131], v[186:187], v[30:31], v[142:143]
	global_store_dwordx4 v208, v[130:133], s[60:61] offset:528
	s_waitcnt vmcnt(12)
	v_pk_fma_f32 v[136:137], v[188:189], v[28:29], v[148:149]
	v_pk_fma_f32 v[134:135], v[186:187], v[26:27], v[146:147]
	global_store_dwordx4 v220, v[134:137], s[60:61] offset:528
	s_waitcnt vmcnt(11)
	v_pk_fma_f32 v[24:25], v[188:189], v[24:25], v[174:175]
	v_pk_fma_f32 v[22:23], v[186:187], v[22:23], v[172:173]
	global_store_dwordx4 v222, v[22:25], s[60:61] offset:528
	s_waitcnt vmcnt(10)
	v_pk_fma_f32 v[16:17], v[188:189], v[16:17], v[202:203]
	v_pk_fma_f32 v[14:15], v[186:187], v[14:15], v[200:201]
	global_store_dwordx4 v228, v[14:17], s[60:61] offset:528
	s_waitcnt vmcnt(9)
	v_pk_fma_f32 v[10:11], v[188:189], v[10:11], v[212:213]
	v_pk_fma_f32 v[8:9], v[186:187], v[8:9], v[210:211]
	global_store_dwordx4 v230, v[8:11], s[60:61] offset:528
	s_waitcnt vmcnt(8)
	v_pk_fma_f32 v[6:7], v[188:189], v[6:7], v[216:217]
	v_pk_fma_f32 v[4:5], v[186:187], v[4:5], v[214:215]
	global_store_dwordx4 v171, v[4:7], s[60:61] offset:528
	s_waitcnt vmcnt(7)
	v_pk_fma_f32 v[2:3], v[188:189], v[2:3], v[226:227]
	v_pk_fma_f32 v[0:1], v[186:187], v[0:1], v[224:225]
	global_store_dwordx4 v176, v[0:3], s[60:61] offset:528
	v_add_u32_e32 v192, s8, v205
	v_ashrrev_i32_e32 v193, 31, v192
	v_add_u32_e32 v190, s8, v241
	v_ashrrev_i32_e32 v191, 31, v190
	v_add_u32_e32 v178, s8, v229
	v_ashrrev_i32_e32 v179, 31, v178
	v_add_u32_e32 v186, s8, v231
	v_ashrrev_i32_e32 v187, 31, v186
	v_add_u32_e32 v164, s8, v240
	v_ashrrev_i32_e32 v165, 31, v164
	v_add_u32_e32 v188, s8, v242
	v_ashrrev_i32_e32 v189, 31, v188
	v_add_u32_e32 v182, s8, v243
	v_ashrrev_i32_e32 v183, 31, v182
	v_add_u32_e32 v180, s8, v244
	v_ashrrev_i32_e32 v181, 31, v180
	s_andn2_b64 vcc, exec, s[90:91]
	v_or_b32_e32 v196, 0x80, v184
	v_ashrrev_i32_e32 v197, 31, v196
	s_cbranch_vccnz .LBB0_1251
	v_mul_f32_e32 v26, v79, v79
	v_mul_f32_e32 v27, v81, v81
	v_fmac_f32_e32 v26, v78, v78
	v_fmac_f32_e32 v27, v80, v80
	v_add_f32_e32 v26, v26, v27
	v_mul_f32_e32 v27, v107, v107
	v_mul_f32_e32 v28, v109, v109
	v_fmac_f32_e32 v27, v106, v106
	v_fmac_f32_e32 v28, v108, v108
	v_add_f32_e32 v27, v27, v28
	v_add_f32_e32 v26, v26, v27
	v_mul_f32_e32 v27, v103, v103
	v_mul_f32_e32 v28, v105, v105
	v_fmac_f32_e32 v27, v102, v102
	v_fmac_f32_e32 v28, v104, v104
	v_add_f32_e32 v27, v27, v28
	v_add_f32_e32 v26, v26, v27
	v_mul_f32_e32 v27, v35, v35
	v_mul_f32_e32 v28, v37, v37
	v_fmac_f32_e32 v27, v34, v34
	v_fmac_f32_e32 v28, v36, v36
	v_add_f32_e32 v27, v27, v28
	v_add_f32_e32 v26, v26, v27
	ds_bpermute_b32 v27, v169, v26
	s_waitcnt lgkmcnt(0)
	s_barrier
	s_waitcnt lgkmcnt(0)
	v_add_f32_e32 v26, v26, v27
	ds_bpermute_b32 v27, v170, v26
	s_and_saveexec_b64 s[8:9], s[0:1]
	s_cbranch_execz .LBB0_1223
	s_waitcnt lgkmcnt(0)
	v_add_f32_e32 v26, v26, v27
	ds_write_b32 v168, v26
